# phase-4 EpiMerge final epilogue: all 16 gate loads issued up front (vmcnt(15) counted waits) instead of a load/wait ladder; plus mid-hook pipelining
# baseline (speedup 1.0000x reference)
.LBB0_957:
	v_or_b32_e32 v146, s45, v159
	v_add_u32_e32 v148, s44, v157
	v_ashrrev_i32_e32 v147, 31, v146
	v_mov_b64_e32 v[150:151], s[10:11]
	v_lshlrev_b64 v[146:147], 1, v[146:147]
	v_mad_i64_i32 v[152:153], s[18:19], v148, s39, v[150:151]
	v_lshl_add_u64 v[162:163], v[152:153], 0, v[146:147]
	s_mov_b32 s98, 0xa6000
	s_mov_b32 s99, 0
	v_lshl_add_u64 v[232:233], v[162:163], 0, 0
	global_load_dwordx4 v[166:169], v[232:233], off
	global_load_dwordx4 v[170:173], v[232:233], off offset:256
	v_lshl_add_u64 v[232:233], v[232:233], 0, s[98:99]
	global_load_dwordx4 v[174:177], v[232:233], off
	global_load_dwordx4 v[178:181], v[232:233], off offset:256
	v_lshl_add_u64 v[232:233], v[232:233], 0, s[98:99]
	global_load_dwordx4 v[182:185], v[232:233], off
	global_load_dwordx4 v[186:189], v[232:233], off offset:256
	v_lshl_add_u64 v[232:233], v[232:233], 0, s[98:99]
	global_load_dwordx4 v[190:193], v[232:233], off
	global_load_dwordx4 v[194:197], v[232:233], off offset:256
	s_mov_b32 s98, 0x33e000
	v_lshl_add_u64 v[232:233], v[232:233], 0, s[98:99]
	s_mov_b32 s98, 0xa6000
	global_load_dwordx4 v[198:201], v[232:233], off
	global_load_dwordx4 v[202:205], v[232:233], off offset:256
	v_lshl_add_u64 v[232:233], v[232:233], 0, s[98:99]
	global_load_dwordx4 v[206:209], v[232:233], off
	global_load_dwordx4 v[210:213], v[232:233], off offset:256
	v_lshl_add_u64 v[232:233], v[232:233], 0, s[98:99]
	global_load_dwordx4 v[214:217], v[232:233], off
	global_load_dwordx4 v[218:221], v[232:233], off offset:256
	v_lshl_add_u64 v[232:233], v[232:233], 0, s[98:99]
	global_load_dwordx4 v[222:225], v[232:233], off
	global_load_dwordx4 v[226:229], v[232:233], off offset:256
	s_and_b64 vcc, exec, s[6:7]
	s_mov_b64 s[6:7], -1
	s_waitcnt vmcnt(15)
	v_lshlrev_b32_e32 v149, 16, v166
	v_and_b32_e32 v152, 0xffff0000, v166
	v_lshlrev_b32_e32 v161, 16, v167
	v_and_b32_e32 v153, 0xffff0000, v167
	v_lshlrev_b32_e32 v165, 16, v169
	v_and_b32_e32 v155, 0xffff0000, v169
	v_lshlrev_b32_e32 v164, 16, v168
	v_and_b32_e32 v154, 0xffff0000, v168
	v_mul_f32_e32 v126, v126, v149
	v_mul_f32_e32 v127, v127, v152
	v_mul_f32_e32 v128, v128, v161
	v_mul_f32_e32 v129, v129, v153
	v_mul_f32_e32 v125, v125, v155
	v_mul_f32_e32 v149, v122, v164
	v_mul_f32_e32 v152, v123, v154
	v_mul_f32_e32 v153, v124, v165
	v_cvt_pk_bf16_f32 v122, v126, v127
	v_cvt_pk_bf16_f32 v123, v128, v129
	v_cvt_pk_bf16_f32 v124, v149, v152
	v_cvt_pk_bf16_f32 v125, v153, v125
	v_ashrrev_i32_e32 v149, 31, v148
	v_lshlrev_b64 v[154:155], 12, v[148:149]
	v_lshl_add_u64 v[154:155], s[8:9], 0, v[154:155]
	v_or_b32_e32 v152, 16, v148
	v_lshl_add_u64 v[154:155], v[154:155], 0, v[146:147]
	v_mad_i64_i32 v[162:163], s[18:19], v152, s39, v[150:151]
	global_store_dwordx4 v[154:155], v[122:125], off
	v_lshl_add_u64 v[162:163], v[162:163], 0, v[146:147]
	v_ashrrev_i32_e32 v153, 31, v152
	s_waitcnt vmcnt(15)
	v_lshlrev_b32_e32 v122, 16, v170
	v_and_b32_e32 v123, 0xffff0000, v170
	v_lshlrev_b32_e32 v124, 16, v171
	v_and_b32_e32 v125, 0xffff0000, v171
	v_lshlrev_b32_e32 v126, 16, v172
	v_and_b32_e32 v127, 0xffff0000, v172
	v_lshlrev_b32_e32 v128, 16, v173
	v_and_b32_e32 v129, 0xffff0000, v173
	v_mul_f32_e32 v118, v118, v122
	v_mul_f32_e32 v119, v119, v123
	v_mul_f32_e32 v120, v120, v124
	v_mul_f32_e32 v121, v121, v125
	v_mul_f32_e32 v113, v113, v129
	v_mul_f32_e32 v122, v110, v126
	v_mul_f32_e32 v123, v111, v127
	v_mul_f32_e32 v124, v112, v128
	v_cvt_pk_bf16_f32 v110, v118, v119
	v_cvt_pk_bf16_f32 v111, v120, v121
	v_cvt_pk_bf16_f32 v112, v122, v123
	v_cvt_pk_bf16_f32 v113, v124, v113
	s_nop 0
	global_store_dwordx4 v[154:155], v[110:113], off offset:256
	s_waitcnt vmcnt(15)
	s_nop 0
	v_lshlrev_b32_e32 v110, 16, v174
	v_and_b32_e32 v111, 0xffff0000, v174
	v_lshlrev_b32_e32 v112, 16, v175
	v_and_b32_e32 v113, 0xffff0000, v175
	v_lshlrev_b32_e32 v118, 16, v176
	v_and_b32_e32 v119, 0xffff0000, v176
	v_lshlrev_b32_e32 v120, 16, v177
	v_and_b32_e32 v121, 0xffff0000, v177
	v_mul_f32_e32 v110, v114, v110
	v_mul_f32_e32 v111, v115, v111
	v_mul_f32_e32 v112, v116, v112
	v_mul_f32_e32 v113, v117, v113
	v_mul_f32_e32 v109, v109, v121
	v_mul_f32_e32 v114, v106, v118
	v_mul_f32_e32 v115, v107, v119
	v_mul_f32_e32 v116, v108, v120
	v_cvt_pk_bf16_f32 v106, v110, v111
	v_cvt_pk_bf16_f32 v107, v112, v113
	v_cvt_pk_bf16_f32 v108, v114, v115
	v_cvt_pk_bf16_f32 v109, v116, v109
	v_lshlrev_b64 v[118:119], 12, v[152:153]
	v_lshl_add_u64 v[118:119], s[8:9], 0, v[118:119]
	v_or_b32_e32 v114, 32, v148
	v_lshl_add_u64 v[118:119], v[118:119], 0, v[146:147]
	v_mad_i64_i32 v[116:117], s[18:19], v114, s39, v[150:151]
	global_store_dwordx4 v[118:119], v[106:109], off
	v_lshl_add_u64 v[116:117], v[116:117], 0, v[146:147]
	v_ashrrev_i32_e32 v115, 31, v114
	s_waitcnt vmcnt(15)
	v_lshlrev_b32_e32 v106, 16, v178
	v_and_b32_e32 v107, 0xffff0000, v178
	v_lshlrev_b32_e32 v108, 16, v179
	v_and_b32_e32 v109, 0xffff0000, v179
	v_lshlrev_b32_e32 v110, 16, v180
	v_and_b32_e32 v111, 0xffff0000, v180
	v_lshlrev_b32_e32 v112, 16, v181
	v_and_b32_e32 v113, 0xffff0000, v181
	v_mul_f32_e32 v102, v102, v106
	v_mul_f32_e32 v103, v103, v107
	v_mul_f32_e32 v104, v104, v108
	v_mul_f32_e32 v105, v105, v109
	v_mul_f32_e32 v97, v97, v113
	v_mul_f32_e32 v106, v94, v110
	v_mul_f32_e32 v107, v95, v111
	v_mul_f32_e32 v108, v96, v112
	v_cvt_pk_bf16_f32 v94, v102, v103
	v_cvt_pk_bf16_f32 v95, v104, v105
	v_cvt_pk_bf16_f32 v96, v106, v107
	v_cvt_pk_bf16_f32 v97, v108, v97
	s_nop 0
	global_store_dwordx4 v[118:119], v[94:97], off offset:256
	s_waitcnt vmcnt(15)
	s_nop 0
	v_lshlrev_b32_e32 v94, 16, v182
	v_and_b32_e32 v95, 0xffff0000, v182
	v_lshlrev_b32_e32 v96, 16, v183
	v_and_b32_e32 v97, 0xffff0000, v183
	v_lshlrev_b32_e32 v102, 16, v184
	v_and_b32_e32 v103, 0xffff0000, v184
	v_lshlrev_b32_e32 v104, 16, v185
	v_and_b32_e32 v105, 0xffff0000, v185
	v_mul_f32_e32 v94, v98, v94
	v_mul_f32_e32 v95, v99, v95
	v_mul_f32_e32 v96, v100, v96
	v_mul_f32_e32 v97, v101, v97
	v_mul_f32_e32 v93, v93, v105
	v_mul_f32_e32 v98, v90, v102
	v_mul_f32_e32 v99, v91, v103
	v_mul_f32_e32 v100, v92, v104
	v_cvt_pk_bf16_f32 v90, v94, v95
	v_cvt_pk_bf16_f32 v91, v96, v97
	v_cvt_pk_bf16_f32 v92, v98, v99
	v_cvt_pk_bf16_f32 v93, v100, v93
	v_lshlrev_b64 v[102:103], 12, v[114:115]
	v_lshl_add_u64 v[102:103], s[8:9], 0, v[102:103]
	v_or_b32_e32 v98, 48, v148
	v_lshl_add_u64 v[102:103], v[102:103], 0, v[146:147]
	v_mad_i64_i32 v[100:101], s[18:19], v98, s39, v[150:151]
	global_store_dwordx4 v[102:103], v[90:93], off
	v_lshl_add_u64 v[100:101], v[100:101], 0, v[146:147]
	v_ashrrev_i32_e32 v99, 31, v98
	s_waitcnt vmcnt(15)
	v_lshlrev_b32_e32 v90, 16, v186
	v_and_b32_e32 v91, 0xffff0000, v186
	v_lshlrev_b32_e32 v92, 16, v187
	v_and_b32_e32 v93, 0xffff0000, v187
	v_lshlrev_b32_e32 v94, 16, v188
	v_and_b32_e32 v95, 0xffff0000, v188
	v_lshlrev_b32_e32 v96, 16, v189
	v_and_b32_e32 v97, 0xffff0000, v189
	v_mul_f32_e32 v86, v86, v90
	v_mul_f32_e32 v87, v87, v91
	v_mul_f32_e32 v88, v88, v92
	v_mul_f32_e32 v89, v89, v93
	v_mul_f32_e32 v81, v81, v97
	v_mul_f32_e32 v90, v78, v94
	v_mul_f32_e32 v91, v79, v95
	v_mul_f32_e32 v92, v80, v96
	v_cvt_pk_bf16_f32 v78, v86, v87
	v_cvt_pk_bf16_f32 v79, v88, v89
	v_cvt_pk_bf16_f32 v80, v90, v91
	v_cvt_pk_bf16_f32 v81, v92, v81
	s_nop 0
	global_store_dwordx4 v[102:103], v[78:81], off offset:256
	s_waitcnt vmcnt(15)
	s_nop 0
	v_lshlrev_b32_e32 v78, 16, v190
	v_and_b32_e32 v79, 0xffff0000, v190
	v_lshlrev_b32_e32 v80, 16, v191
	v_and_b32_e32 v81, 0xffff0000, v191
	v_lshlrev_b32_e32 v86, 16, v192
	v_and_b32_e32 v87, 0xffff0000, v192
	v_lshlrev_b32_e32 v88, 16, v193
	v_and_b32_e32 v89, 0xffff0000, v193
	v_mul_f32_e32 v78, v82, v78
	v_mul_f32_e32 v79, v83, v79
	v_mul_f32_e32 v80, v84, v80
	v_mul_f32_e32 v81, v85, v81
	v_mul_f32_e32 v77, v77, v89
	v_mul_f32_e32 v82, v74, v86
	v_mul_f32_e32 v83, v75, v87
	v_mul_f32_e32 v84, v76, v88
	v_cvt_pk_bf16_f32 v74, v78, v79
	v_cvt_pk_bf16_f32 v75, v80, v81
	v_cvt_pk_bf16_f32 v76, v82, v83
	v_cvt_pk_bf16_f32 v77, v84, v77
	v_lshlrev_b64 v[86:87], 12, v[98:99]
	v_lshl_add_u64 v[86:87], s[8:9], 0, v[86:87]
	v_add_u32_e32 v82, 0x80, v148
	v_lshl_add_u64 v[86:87], v[86:87], 0, v[146:147]
	v_mad_i64_i32 v[84:85], s[18:19], v82, s39, v[150:151]
	global_store_dwordx4 v[86:87], v[74:77], off
	v_lshl_add_u64 v[84:85], v[84:85], 0, v[146:147]
	v_ashrrev_i32_e32 v83, 31, v82
	s_waitcnt vmcnt(15)
	v_lshlrev_b32_e32 v74, 16, v194
	v_and_b32_e32 v75, 0xffff0000, v194
	v_lshlrev_b32_e32 v76, 16, v195
	v_and_b32_e32 v77, 0xffff0000, v195
	v_lshlrev_b32_e32 v78, 16, v196
	v_and_b32_e32 v79, 0xffff0000, v196
	v_lshlrev_b32_e32 v80, 16, v197
	v_and_b32_e32 v81, 0xffff0000, v197
	v_mul_f32_e32 v70, v70, v74
	v_mul_f32_e32 v71, v71, v75
	v_mul_f32_e32 v72, v72, v76
	v_mul_f32_e32 v73, v73, v77
	v_mul_f32_e32 v69, v69, v81
	v_mul_f32_e32 v74, v66, v78
	v_mul_f32_e32 v75, v67, v79
	v_mul_f32_e32 v76, v68, v80
	v_cvt_pk_bf16_f32 v66, v70, v71
	v_cvt_pk_bf16_f32 v67, v72, v73
	v_cvt_pk_bf16_f32 v68, v74, v75
	v_cvt_pk_bf16_f32 v69, v76, v69
	s_nop 0
	global_store_dwordx4 v[86:87], v[66:69], off offset:256
	s_waitcnt vmcnt(15)
	s_nop 0
	v_lshlrev_b32_e32 v66, 16, v198
	v_and_b32_e32 v67, 0xffff0000, v198
	v_lshlrev_b32_e32 v68, 16, v199
	v_and_b32_e32 v69, 0xffff0000, v199
	v_lshlrev_b32_e32 v70, 16, v200
	v_and_b32_e32 v71, 0xffff0000, v200
	v_lshlrev_b32_e32 v72, 16, v201
	v_and_b32_e32 v73, 0xffff0000, v201
	v_mul_f32_e32 v62, v62, v66
	v_mul_f32_e32 v63, v63, v67
	v_mul_f32_e32 v64, v64, v68
	v_mul_f32_e32 v65, v65, v69
	v_mul_f32_e32 v61, v61, v73
	v_mul_f32_e32 v66, v58, v70
	v_mul_f32_e32 v67, v59, v71
	v_mul_f32_e32 v68, v60, v72
	v_cvt_pk_bf16_f32 v58, v62, v63
	v_cvt_pk_bf16_f32 v59, v64, v65
	v_cvt_pk_bf16_f32 v60, v66, v67
	v_cvt_pk_bf16_f32 v61, v68, v61
	v_lshlrev_b64 v[70:71], 12, v[82:83]
	v_lshl_add_u64 v[70:71], s[8:9], 0, v[70:71]
	v_add_u32_e32 v66, 0x90, v148
	v_lshl_add_u64 v[70:71], v[70:71], 0, v[146:147]
	v_mad_i64_i32 v[68:69], s[18:19], v66, s39, v[150:151]
	global_store_dwordx4 v[70:71], v[58:61], off
	v_lshl_add_u64 v[68:69], v[68:69], 0, v[146:147]
	v_ashrrev_i32_e32 v67, 31, v66
	s_waitcnt vmcnt(15)
	v_lshlrev_b32_e32 v58, 16, v202
	v_and_b32_e32 v59, 0xffff0000, v202
	v_lshlrev_b32_e32 v60, 16, v203
	v_and_b32_e32 v61, 0xffff0000, v203
	v_lshlrev_b32_e32 v62, 16, v204
	v_and_b32_e32 v63, 0xffff0000, v204
	v_lshlrev_b32_e32 v64, 16, v205
	v_and_b32_e32 v65, 0xffff0000, v205
	v_mul_f32_e32 v54, v54, v58
	v_mul_f32_e32 v55, v55, v59
	v_mul_f32_e32 v56, v56, v60
	v_mul_f32_e32 v57, v57, v61
	v_mul_f32_e32 v49, v49, v65
	v_mul_f32_e32 v58, v46, v62
	v_mul_f32_e32 v59, v47, v63
	v_mul_f32_e32 v60, v48, v64
	v_cvt_pk_bf16_f32 v46, v54, v55
	v_cvt_pk_bf16_f32 v47, v56, v57
	v_cvt_pk_bf16_f32 v48, v58, v59
	v_cvt_pk_bf16_f32 v49, v60, v49
	s_nop 0
	global_store_dwordx4 v[70:71], v[46:49], off offset:256
	s_waitcnt vmcnt(15)
	s_nop 0
	v_lshlrev_b32_e32 v46, 16, v206
	v_and_b32_e32 v47, 0xffff0000, v206
	v_lshlrev_b32_e32 v48, 16, v207
	v_and_b32_e32 v49, 0xffff0000, v207
	v_lshlrev_b32_e32 v54, 16, v208
	v_and_b32_e32 v55, 0xffff0000, v208
	v_lshlrev_b32_e32 v56, 16, v209
	v_and_b32_e32 v57, 0xffff0000, v209
	v_mul_f32_e32 v46, v50, v46
	v_mul_f32_e32 v47, v51, v47
	v_mul_f32_e32 v48, v52, v48
	v_mul_f32_e32 v49, v53, v49
	v_mul_f32_e32 v45, v45, v57
	v_mul_f32_e32 v50, v42, v54
	v_mul_f32_e32 v51, v43, v55
	v_mul_f32_e32 v52, v44, v56
	v_cvt_pk_bf16_f32 v42, v46, v47
	v_cvt_pk_bf16_f32 v43, v48, v49
	v_cvt_pk_bf16_f32 v44, v50, v51
	v_cvt_pk_bf16_f32 v45, v52, v45
	v_lshlrev_b64 v[54:55], 12, v[66:67]
	v_lshl_add_u64 v[54:55], s[8:9], 0, v[54:55]
	v_add_u32_e32 v50, 0xa0, v148
	v_lshl_add_u64 v[54:55], v[54:55], 0, v[146:147]
	v_mad_i64_i32 v[52:53], s[18:19], v50, s39, v[150:151]
	global_store_dwordx4 v[54:55], v[42:45], off
	v_lshl_add_u64 v[52:53], v[52:53], 0, v[146:147]
	v_ashrrev_i32_e32 v51, 31, v50
	s_waitcnt vmcnt(15)
	v_lshlrev_b32_e32 v42, 16, v210
	v_and_b32_e32 v43, 0xffff0000, v210
	v_lshlrev_b32_e32 v44, 16, v211
	v_and_b32_e32 v45, 0xffff0000, v211
	v_lshlrev_b32_e32 v46, 16, v212
	v_and_b32_e32 v47, 0xffff0000, v212
	v_lshlrev_b32_e32 v48, 16, v213
	v_and_b32_e32 v49, 0xffff0000, v213
	v_mul_f32_e32 v38, v38, v42
	v_mul_f32_e32 v39, v39, v43
	v_mul_f32_e32 v40, v40, v44
	v_mul_f32_e32 v41, v41, v45
	v_mul_f32_e32 v33, v33, v49
	v_mul_f32_e32 v42, v30, v46
	v_mul_f32_e32 v43, v31, v47
	v_mul_f32_e32 v44, v32, v48
	v_cvt_pk_bf16_f32 v30, v38, v39
	v_cvt_pk_bf16_f32 v31, v40, v41
	v_cvt_pk_bf16_f32 v32, v42, v43
	v_cvt_pk_bf16_f32 v33, v44, v33
	s_nop 0
	global_store_dwordx4 v[54:55], v[30:33], off offset:256
	s_waitcnt vmcnt(15)
	s_nop 0
	v_lshlrev_b32_e32 v30, 16, v214
	v_and_b32_e32 v31, 0xffff0000, v214
	v_lshlrev_b32_e32 v32, 16, v215
	v_and_b32_e32 v33, 0xffff0000, v215
	v_lshlrev_b32_e32 v38, 16, v216
	v_and_b32_e32 v39, 0xffff0000, v216
	v_lshlrev_b32_e32 v40, 16, v217
	v_and_b32_e32 v41, 0xffff0000, v217
	v_mul_f32_e32 v30, v34, v30
	v_mul_f32_e32 v31, v35, v31
	v_mul_f32_e32 v32, v36, v32
	v_mul_f32_e32 v33, v37, v33
	v_mul_f32_e32 v29, v29, v41
	v_mul_f32_e32 v34, v26, v38
	v_mul_f32_e32 v35, v27, v39
	v_mul_f32_e32 v36, v28, v40
	v_cvt_pk_bf16_f32 v26, v30, v31
	v_cvt_pk_bf16_f32 v27, v32, v33
	v_cvt_pk_bf16_f32 v28, v34, v35
	v_cvt_pk_bf16_f32 v29, v36, v29
	v_lshlrev_b64 v[38:39], 12, v[50:51]
	v_lshl_add_u64 v[38:39], s[8:9], 0, v[38:39]
	v_add_u32_e32 v34, 0xb0, v148
	v_lshl_add_u64 v[38:39], v[38:39], 0, v[146:147]
	v_mad_i64_i32 v[36:37], s[18:19], v34, s39, v[150:151]
	global_store_dwordx4 v[38:39], v[26:29], off
	v_lshl_add_u64 v[36:37], v[36:37], 0, v[146:147]
	v_ashrrev_i32_e32 v35, 31, v34
	s_waitcnt vmcnt(15)
	v_lshlrev_b32_e32 v26, 16, v218
	v_and_b32_e32 v27, 0xffff0000, v218
	v_lshlrev_b32_e32 v28, 16, v219
	v_and_b32_e32 v29, 0xffff0000, v219
	v_lshlrev_b32_e32 v30, 16, v220
	v_and_b32_e32 v31, 0xffff0000, v220
	v_lshlrev_b32_e32 v32, 16, v221
	v_and_b32_e32 v33, 0xffff0000, v221
	v_mul_f32_e32 v22, v22, v26
	v_mul_f32_e32 v23, v23, v27
	v_mul_f32_e32 v24, v24, v28
	v_mul_f32_e32 v25, v25, v29
	v_mul_f32_e32 v17, v17, v33
	v_mul_f32_e32 v26, v14, v30
	v_mul_f32_e32 v27, v15, v31
	v_mul_f32_e32 v28, v16, v32
	v_cvt_pk_bf16_f32 v14, v22, v23
	v_cvt_pk_bf16_f32 v15, v24, v25
	v_cvt_pk_bf16_f32 v16, v26, v27
	v_cvt_pk_bf16_f32 v17, v28, v17
	s_nop 0
	global_store_dwordx4 v[38:39], v[14:17], off offset:256
	s_waitcnt vmcnt(15)
	s_nop 0
	v_lshlrev_b32_e32 v14, 16, v222
	v_and_b32_e32 v15, 0xffff0000, v222
	v_lshlrev_b32_e32 v16, 16, v223
	v_and_b32_e32 v17, 0xffff0000, v223
	v_lshlrev_b32_e32 v22, 16, v224
	v_and_b32_e32 v23, 0xffff0000, v224
	v_lshlrev_b32_e32 v24, 16, v225
	v_and_b32_e32 v25, 0xffff0000, v225
	v_mul_f32_e32 v14, v18, v14
	v_mul_f32_e32 v15, v19, v15
	v_mul_f32_e32 v16, v20, v16
	v_mul_f32_e32 v17, v21, v17
	v_mul_f32_e32 v13, v13, v25
	v_mul_f32_e32 v18, v10, v22
	v_mul_f32_e32 v19, v11, v23
	v_mul_f32_e32 v20, v12, v24
	v_cvt_pk_bf16_f32 v10, v14, v15
	v_cvt_pk_bf16_f32 v11, v16, v17
	v_cvt_pk_bf16_f32 v12, v18, v19
	v_cvt_pk_bf16_f32 v13, v20, v13
	v_lshlrev_b64 v[18:19], 12, v[34:35]
	v_lshl_add_u64 v[18:19], s[8:9], 0, v[18:19]
	v_lshl_add_u64 v[18:19], v[18:19], 0, v[146:147]
	global_store_dwordx4 v[18:19], v[10:13], off
	s_waitcnt vmcnt(15)
	s_nop 0
	v_lshlrev_b32_e32 v10, 16, v226
	v_and_b32_e32 v11, 0xffff0000, v226
	v_lshlrev_b32_e32 v12, 16, v227
	v_and_b32_e32 v13, 0xffff0000, v227
	v_lshlrev_b32_e32 v14, 16, v228
	v_and_b32_e32 v15, 0xffff0000, v228
	v_lshlrev_b32_e32 v16, 16, v229
	v_and_b32_e32 v17, 0xffff0000, v229
	v_mul_f32_e32 v5, v5, v17
	v_mul_f32_e32 v6, v6, v10
	v_mul_f32_e32 v7, v7, v11
	v_mul_f32_e32 v8, v8, v12
	v_mul_f32_e32 v9, v9, v13
	v_mul_f32_e32 v10, v2, v14
	v_mul_f32_e32 v11, v3, v15
	v_mul_f32_e32 v12, v4, v16
	v_cvt_pk_bf16_f32 v2, v6, v7
	v_cvt_pk_bf16_f32 v3, v8, v9
	v_cvt_pk_bf16_f32 v4, v10, v11
	v_cvt_pk_bf16_f32 v5, v12, v5
	global_store_dwordx4 v[18:19], v[2:5], off offset:256
	s_cbranch_vccnz .LBB0_940
	s_andn2_b64 vcc, exec, s[0:1]
	s_cbranch_vccnz .LBB0_939
	s_barrier
	s_branch .LBB0_939
